# P1 SwiGLU epilogue with packed f32 multiplies/adds (same op order per element)
# baseline (speedup 1.0000x reference)
.LBB0_125:
	v_mov_b32_e32 v160, 0xbfb8aa3b
	v_pk_mul_f32 v[156:157], v[126:127], v[160:161] op_sel_hi:[1,0]
	v_pk_mul_f32 v[158:159], v[128:129], v[160:161] op_sel_hi:[1,0]
	v_exp_f32_e32 v156, v156
	v_exp_f32_e32 v157, v157
	v_exp_f32_e32 v158, v158
	v_exp_f32_e32 v159, v159
	v_pk_add_f32 v[156:157], v[156:157], 1.0 op_sel_hi:[1,0]
	s_nop 0
	v_pk_add_f32 v[158:159], v[158:159], 1.0 op_sel_hi:[1,0]
	v_rcp_f32_e32 v156, v156
	v_rcp_f32_e32 v157, v157
	v_rcp_f32_e32 v158, v158
	v_rcp_f32_e32 v159, v159
	v_pk_mul_f32 v[126:127], v[126:127], v[156:157]
	s_nop 0
	v_pk_mul_f32 v[128:129], v[128:129], v[158:159]
	v_pk_mul_f32 v[118:119], v[118:119], v[126:127]
	v_pk_mul_f32 v[120:121], v[120:121], v[128:129]
	v_pk_mul_f32 v[156:157], v[122:123], v[160:161] op_sel_hi:[1,0]
	v_pk_mul_f32 v[158:159], v[124:125], v[160:161] op_sel_hi:[1,0]
	v_exp_f32_e32 v156, v156
	v_exp_f32_e32 v157, v157
	v_exp_f32_e32 v158, v158
	v_exp_f32_e32 v159, v159
	v_pk_add_f32 v[156:157], v[156:157], 1.0 op_sel_hi:[1,0]
	s_nop 0
	v_pk_add_f32 v[158:159], v[158:159], 1.0 op_sel_hi:[1,0]
	v_rcp_f32_e32 v156, v156
	v_rcp_f32_e32 v157, v157
	v_rcp_f32_e32 v158, v158
	v_rcp_f32_e32 v159, v159
	v_pk_mul_f32 v[122:123], v[122:123], v[156:157]
	s_nop 0
	v_pk_mul_f32 v[124:125], v[124:125], v[158:159]
	v_pk_mul_f32 v[114:115], v[114:115], v[122:123]
	v_pk_mul_f32 v[116:117], v[116:117], v[124:125]
	v_cvt_pk_bf16_f32 v118, v118, v119
	v_cvt_pk_bf16_f32 v119, v120, v121
	v_cvt_pk_bf16_f32 v120, v114, v115
	v_cvt_pk_bf16_f32 v121, v116, v117
	v_pk_mul_f32 v[156:157], v[110:111], v[160:161] op_sel_hi:[1,0]
	v_pk_mul_f32 v[158:159], v[112:113], v[160:161] op_sel_hi:[1,0]
	v_exp_f32_e32 v156, v156
	v_exp_f32_e32 v157, v157
	v_exp_f32_e32 v158, v158
	v_exp_f32_e32 v159, v159
	v_pk_add_f32 v[156:157], v[156:157], 1.0 op_sel_hi:[1,0]
	s_nop 0
	v_pk_add_f32 v[158:159], v[158:159], 1.0 op_sel_hi:[1,0]
	v_rcp_f32_e32 v156, v156
	v_rcp_f32_e32 v157, v157
	v_rcp_f32_e32 v158, v158
	v_rcp_f32_e32 v159, v159
	v_pk_mul_f32 v[110:111], v[110:111], v[156:157]
	s_nop 0
	v_pk_mul_f32 v[112:113], v[112:113], v[158:159]
	v_pk_mul_f32 v[102:103], v[102:103], v[110:111]
	v_pk_mul_f32 v[104:105], v[104:105], v[112:113]
	v_pk_mul_f32 v[156:157], v[106:107], v[160:161] op_sel_hi:[1,0]
	v_pk_mul_f32 v[158:159], v[108:109], v[160:161] op_sel_hi:[1,0]
	v_exp_f32_e32 v156, v156
	v_exp_f32_e32 v157, v157
	v_exp_f32_e32 v158, v158
	v_exp_f32_e32 v159, v159
	v_pk_add_f32 v[156:157], v[156:157], 1.0 op_sel_hi:[1,0]
	s_nop 0
	v_pk_add_f32 v[158:159], v[158:159], 1.0 op_sel_hi:[1,0]
	v_rcp_f32_e32 v156, v156
	v_rcp_f32_e32 v157, v157
	v_rcp_f32_e32 v158, v158
	v_rcp_f32_e32 v159, v159
	v_pk_mul_f32 v[106:107], v[106:107], v[156:157]
	s_nop 0
	v_pk_mul_f32 v[108:109], v[108:109], v[158:159]
	v_pk_mul_f32 v[98:99], v[98:99], v[106:107]
	v_pk_mul_f32 v[100:101], v[100:101], v[108:109]
	v_cvt_pk_bf16_f32 v101, v100, v101
	v_cvt_pk_bf16_f32 v100, v98, v99
	v_cvt_pk_bf16_f32 v98, v102, v103
	v_cvt_pk_bf16_f32 v99, v104, v105
	v_pk_mul_f32 v[156:157], v[94:95], v[160:161] op_sel_hi:[1,0]
	v_pk_mul_f32 v[158:159], v[96:97], v[160:161] op_sel_hi:[1,0]
	v_exp_f32_e32 v156, v156
	v_exp_f32_e32 v157, v157
	v_exp_f32_e32 v158, v158
	v_exp_f32_e32 v159, v159
	v_pk_add_f32 v[156:157], v[156:157], 1.0 op_sel_hi:[1,0]
	s_nop 0
	v_pk_add_f32 v[158:159], v[158:159], 1.0 op_sel_hi:[1,0]
	v_rcp_f32_e32 v156, v156
	v_rcp_f32_e32 v157, v157
	v_rcp_f32_e32 v158, v158
	v_rcp_f32_e32 v159, v159
	v_pk_mul_f32 v[94:95], v[94:95], v[156:157]
	s_nop 0
	v_pk_mul_f32 v[96:97], v[96:97], v[158:159]
	v_pk_mul_f32 v[86:87], v[86:87], v[94:95]
	v_pk_mul_f32 v[88:89], v[88:89], v[96:97]
	v_pk_mul_f32 v[156:157], v[90:91], v[160:161] op_sel_hi:[1,0]
	v_pk_mul_f32 v[158:159], v[92:93], v[160:161] op_sel_hi:[1,0]
	v_exp_f32_e32 v156, v156
	v_exp_f32_e32 v157, v157
	v_exp_f32_e32 v158, v158
	v_exp_f32_e32 v159, v159
	v_pk_add_f32 v[156:157], v[156:157], 1.0 op_sel_hi:[1,0]
	s_nop 0
	v_pk_add_f32 v[158:159], v[158:159], 1.0 op_sel_hi:[1,0]
	v_rcp_f32_e32 v156, v156
	v_rcp_f32_e32 v157, v157
	v_rcp_f32_e32 v158, v158
	v_rcp_f32_e32 v159, v159
	v_pk_mul_f32 v[90:91], v[90:91], v[156:157]
	s_nop 0
	v_pk_mul_f32 v[92:93], v[92:93], v[158:159]
	v_pk_mul_f32 v[82:83], v[82:83], v[90:91]
	v_pk_mul_f32 v[84:85], v[84:85], v[92:93]
	v_cvt_pk_bf16_f32 v85, v84, v85
	v_cvt_pk_bf16_f32 v84, v82, v83
	v_cvt_pk_bf16_f32 v82, v86, v87
	v_cvt_pk_bf16_f32 v83, v88, v89
	v_pk_mul_f32 v[156:157], v[78:79], v[160:161] op_sel_hi:[1,0]
	v_pk_mul_f32 v[158:159], v[80:81], v[160:161] op_sel_hi:[1,0]
	v_exp_f32_e32 v156, v156
	v_exp_f32_e32 v157, v157
	v_exp_f32_e32 v158, v158
	v_exp_f32_e32 v159, v159
	v_pk_add_f32 v[156:157], v[156:157], 1.0 op_sel_hi:[1,0]
	s_nop 0
	v_pk_add_f32 v[158:159], v[158:159], 1.0 op_sel_hi:[1,0]
	v_rcp_f32_e32 v156, v156
	v_rcp_f32_e32 v157, v157
	v_rcp_f32_e32 v158, v158
	v_rcp_f32_e32 v159, v159
	v_pk_mul_f32 v[78:79], v[78:79], v[156:157]
	s_nop 0
	v_pk_mul_f32 v[80:81], v[80:81], v[158:159]
	v_pk_mul_f32 v[70:71], v[70:71], v[78:79]
	v_pk_mul_f32 v[72:73], v[72:73], v[80:81]
	v_pk_mul_f32 v[156:157], v[74:75], v[160:161] op_sel_hi:[1,0]
	v_pk_mul_f32 v[158:159], v[76:77], v[160:161] op_sel_hi:[1,0]
	v_exp_f32_e32 v156, v156
	v_exp_f32_e32 v157, v157
	v_exp_f32_e32 v158, v158
	v_exp_f32_e32 v159, v159
	v_pk_add_f32 v[156:157], v[156:157], 1.0 op_sel_hi:[1,0]
	s_nop 0
	v_pk_add_f32 v[158:159], v[158:159], 1.0 op_sel_hi:[1,0]
	v_rcp_f32_e32 v156, v156
	v_rcp_f32_e32 v157, v157
	v_rcp_f32_e32 v158, v158
	v_rcp_f32_e32 v159, v159
	v_pk_mul_f32 v[74:75], v[74:75], v[156:157]
	s_nop 0
	v_pk_mul_f32 v[76:77], v[76:77], v[158:159]
	v_pk_mul_f32 v[66:67], v[66:67], v[74:75]
	v_pk_mul_f32 v[68:69], v[68:69], v[76:77]
	v_cvt_pk_bf16_f32 v69, v68, v69
	v_cvt_pk_bf16_f32 v68, v66, v67
	v_cvt_pk_bf16_f32 v66, v70, v71
	v_cvt_pk_bf16_f32 v67, v72, v73
	v_pk_mul_f32 v[156:157], v[62:63], v[160:161] op_sel_hi:[1,0]
	v_pk_mul_f32 v[158:159], v[64:65], v[160:161] op_sel_hi:[1,0]
	v_exp_f32_e32 v156, v156
	v_exp_f32_e32 v157, v157
	v_exp_f32_e32 v158, v158
	v_exp_f32_e32 v159, v159
	v_pk_add_f32 v[156:157], v[156:157], 1.0 op_sel_hi:[1,0]
	s_nop 0
	v_pk_add_f32 v[158:159], v[158:159], 1.0 op_sel_hi:[1,0]
	v_rcp_f32_e32 v156, v156
	v_rcp_f32_e32 v157, v157
	v_rcp_f32_e32 v158, v158
	v_rcp_f32_e32 v159, v159
	v_pk_mul_f32 v[62:63], v[62:63], v[156:157]
	s_nop 0
	v_pk_mul_f32 v[64:65], v[64:65], v[158:159]
	v_pk_mul_f32 v[54:55], v[54:55], v[62:63]
	v_pk_mul_f32 v[56:57], v[56:57], v[64:65]
	v_pk_mul_f32 v[156:157], v[58:59], v[160:161] op_sel_hi:[1,0]
	v_pk_mul_f32 v[158:159], v[60:61], v[160:161] op_sel_hi:[1,0]
	v_exp_f32_e32 v156, v156
	v_exp_f32_e32 v157, v157
	v_exp_f32_e32 v158, v158
	v_exp_f32_e32 v159, v159
	v_pk_add_f32 v[156:157], v[156:157], 1.0 op_sel_hi:[1,0]
	s_nop 0
	v_pk_add_f32 v[158:159], v[158:159], 1.0 op_sel_hi:[1,0]
	v_rcp_f32_e32 v156, v156
	v_rcp_f32_e32 v157, v157
	v_rcp_f32_e32 v158, v158
	v_rcp_f32_e32 v159, v159
	v_pk_mul_f32 v[58:59], v[58:59], v[156:157]
	s_nop 0
	v_pk_mul_f32 v[60:61], v[60:61], v[158:159]
	v_pk_mul_f32 v[50:51], v[50:51], v[58:59]
	v_pk_mul_f32 v[52:53], v[52:53], v[60:61]
	v_cvt_pk_bf16_f32 v53, v52, v53
	v_cvt_pk_bf16_f32 v52, v50, v51
	v_cvt_pk_bf16_f32 v50, v54, v55
	v_cvt_pk_bf16_f32 v51, v56, v57
	v_pk_mul_f32 v[156:157], v[46:47], v[160:161] op_sel_hi:[1,0]
	v_pk_mul_f32 v[158:159], v[48:49], v[160:161] op_sel_hi:[1,0]
	v_exp_f32_e32 v156, v156
	v_exp_f32_e32 v157, v157
	v_exp_f32_e32 v158, v158
	v_exp_f32_e32 v159, v159
	v_pk_add_f32 v[156:157], v[156:157], 1.0 op_sel_hi:[1,0]
	s_nop 0
	v_pk_add_f32 v[158:159], v[158:159], 1.0 op_sel_hi:[1,0]
	v_rcp_f32_e32 v156, v156
	v_rcp_f32_e32 v157, v157
	v_rcp_f32_e32 v158, v158
	v_rcp_f32_e32 v159, v159
	v_pk_mul_f32 v[46:47], v[46:47], v[156:157]
	s_nop 0
	v_pk_mul_f32 v[48:49], v[48:49], v[158:159]
	v_pk_mul_f32 v[38:39], v[38:39], v[46:47]
	v_pk_mul_f32 v[40:41], v[40:41], v[48:49]
	v_pk_mul_f32 v[156:157], v[42:43], v[160:161] op_sel_hi:[1,0]
	v_pk_mul_f32 v[158:159], v[44:45], v[160:161] op_sel_hi:[1,0]
	v_exp_f32_e32 v156, v156
	v_exp_f32_e32 v157, v157
	v_exp_f32_e32 v158, v158
	v_exp_f32_e32 v159, v159
	v_pk_add_f32 v[156:157], v[156:157], 1.0 op_sel_hi:[1,0]
	s_nop 0
	v_pk_add_f32 v[158:159], v[158:159], 1.0 op_sel_hi:[1,0]
	v_rcp_f32_e32 v156, v156
	v_rcp_f32_e32 v157, v157
	v_rcp_f32_e32 v158, v158
	v_rcp_f32_e32 v159, v159
	v_pk_mul_f32 v[42:43], v[42:43], v[156:157]
	s_nop 0
	v_pk_mul_f32 v[44:45], v[44:45], v[158:159]
	v_pk_mul_f32 v[34:35], v[34:35], v[42:43]
	v_pk_mul_f32 v[36:37], v[36:37], v[44:45]
	v_cvt_pk_bf16_f32 v37, v36, v37
	v_cvt_pk_bf16_f32 v36, v34, v35
	v_cvt_pk_bf16_f32 v34, v38, v39
	v_cvt_pk_bf16_f32 v35, v40, v41
	v_pk_mul_f32 v[156:157], v[30:31], v[160:161] op_sel_hi:[1,0]
	v_pk_mul_f32 v[158:159], v[32:33], v[160:161] op_sel_hi:[1,0]
	v_exp_f32_e32 v156, v156
	v_exp_f32_e32 v157, v157
	v_exp_f32_e32 v158, v158
	v_exp_f32_e32 v159, v159
	v_pk_add_f32 v[156:157], v[156:157], 1.0 op_sel_hi:[1,0]
	s_nop 0
	v_pk_add_f32 v[158:159], v[158:159], 1.0 op_sel_hi:[1,0]
	v_rcp_f32_e32 v156, v156
	v_rcp_f32_e32 v157, v157
	v_rcp_f32_e32 v158, v158
	v_rcp_f32_e32 v159, v159
	v_pk_mul_f32 v[30:31], v[30:31], v[156:157]
	s_nop 0
	v_pk_mul_f32 v[32:33], v[32:33], v[158:159]
	v_pk_mul_f32 v[22:23], v[22:23], v[30:31]
	v_pk_mul_f32 v[24:25], v[24:25], v[32:33]
	v_pk_mul_f32 v[156:157], v[26:27], v[160:161] op_sel_hi:[1,0]
	v_pk_mul_f32 v[158:159], v[28:29], v[160:161] op_sel_hi:[1,0]
	v_exp_f32_e32 v156, v156
	v_exp_f32_e32 v157, v157
	v_exp_f32_e32 v158, v158
	v_exp_f32_e32 v159, v159
	v_pk_add_f32 v[156:157], v[156:157], 1.0 op_sel_hi:[1,0]
	s_nop 0
	v_pk_add_f32 v[158:159], v[158:159], 1.0 op_sel_hi:[1,0]
	v_rcp_f32_e32 v156, v156
	v_rcp_f32_e32 v157, v157
	v_rcp_f32_e32 v158, v158
	v_rcp_f32_e32 v159, v159
	v_pk_mul_f32 v[26:27], v[26:27], v[156:157]
	s_nop 0
	v_pk_mul_f32 v[28:29], v[28:29], v[158:159]
	v_pk_mul_f32 v[18:19], v[18:19], v[26:27]
	v_pk_mul_f32 v[20:21], v[20:21], v[28:29]
	v_cvt_pk_bf16_f32 v21, v20, v21
	v_cvt_pk_bf16_f32 v20, v18, v19
	v_cvt_pk_bf16_f32 v18, v22, v23
	v_cvt_pk_bf16_f32 v19, v24, v25
	v_pk_mul_f32 v[156:157], v[14:15], v[160:161] op_sel_hi:[1,0]
	v_pk_mul_f32 v[158:159], v[16:17], v[160:161] op_sel_hi:[1,0]
	v_exp_f32_e32 v156, v156
	v_exp_f32_e32 v157, v157
	v_exp_f32_e32 v158, v158
	v_exp_f32_e32 v159, v159
	v_pk_add_f32 v[156:157], v[156:157], 1.0 op_sel_hi:[1,0]
	s_nop 0
	v_pk_add_f32 v[158:159], v[158:159], 1.0 op_sel_hi:[1,0]
	v_rcp_f32_e32 v156, v156
	v_rcp_f32_e32 v157, v157
	v_rcp_f32_e32 v158, v158
	v_rcp_f32_e32 v159, v159
	v_pk_mul_f32 v[14:15], v[14:15], v[156:157]
	s_nop 0
	v_pk_mul_f32 v[16:17], v[16:17], v[158:159]
	v_pk_mul_f32 v[6:7], v[6:7], v[14:15]
	v_pk_mul_f32 v[8:9], v[8:9], v[16:17]
	v_pk_mul_f32 v[156:157], v[10:11], v[160:161] op_sel_hi:[1,0]
	v_pk_mul_f32 v[158:159], v[12:13], v[160:161] op_sel_hi:[1,0]
	v_exp_f32_e32 v156, v156
	v_exp_f32_e32 v157, v157
	v_exp_f32_e32 v158, v158
	v_exp_f32_e32 v159, v159
	v_pk_add_f32 v[156:157], v[156:157], 1.0 op_sel_hi:[1,0]
	s_nop 0
	v_pk_add_f32 v[158:159], v[158:159], 1.0 op_sel_hi:[1,0]
	v_rcp_f32_e32 v156, v156
	v_rcp_f32_e32 v157, v157
	v_rcp_f32_e32 v158, v158
	v_rcp_f32_e32 v159, v159
	v_pk_mul_f32 v[10:11], v[10:11], v[156:157]
	s_nop 0
	v_pk_mul_f32 v[12:13], v[12:13], v[158:159]
	v_pk_mul_f32 v[2:3], v[2:3], v[10:11]
	v_pk_mul_f32 v[4:5], v[4:5], v[12:13]
	v_cvt_pk_bf16_f32 v5, v4, v5
	v_cvt_pk_bf16_f32 v4, v2, v3
	v_cvt_pk_bf16_f32 v2, v6, v7
	v_cvt_pk_bf16_f32 v3, v8, v9
	v_mov_b32_e32 v151, v1
	v_mov_b32_e32 v152, v146
	s_lshl_b32 s25, s47, 7
	s_lshl_b32 s23, s30, 8
	s_or_b32 s25, s25, s35
	v_lshl_add_u32 v152, v152, 3, s25
	s_add_i32 s23, s23, s34
	v_add_u32_e32 v151, s23, v151
	v_ashrrev_i32_e32 v153, 31, v152
	v_mov_b64_e32 v[114:115], s[8:9]
	v_mad_i64_i32 v[122:123], s[36:37], v151, s46, v[114:115]
	v_lshlrev_b64 v[116:117], 1, v[152:153]
	v_lshl_add_u64 v[122:123], v[122:123], 0, v[116:117]
	global_store_dwordx4 v[122:123], v[118:121], off
	s_andn2_b64 vcc, exec, s[4:5]
	s_mov_b64 s[4:5], -1
	v_add_u32_e32 v120, 16, v151
	v_mad_i64_i32 v[102:103], s[36:37], v120, s46, v[114:115]
	v_lshl_add_u64 v[102:103], v[102:103], 0, v[116:117]
	global_store_dwordx4 v[102:103], v[98:101], off
	s_nop 1
	v_add_u32_e32 v100, 32, v151
	v_mad_i64_i32 v[86:87], s[36:37], v100, s46, v[114:115]
	v_lshl_add_u64 v[86:87], v[86:87], 0, v[116:117]
	global_store_dwordx4 v[86:87], v[82:85], off
	s_nop 1
	v_add_u32_e32 v84, 48, v151
	v_mad_i64_i32 v[70:71], s[36:37], v84, s46, v[114:115]
	v_lshl_add_u64 v[70:71], v[70:71], 0, v[116:117]
	global_store_dwordx4 v[70:71], v[66:69], off
	s_nop 1
	v_add_u32_e32 v68, 0x80, v151
	v_mad_i64_i32 v[54:55], s[36:37], v68, s46, v[114:115]
	v_lshl_add_u64 v[54:55], v[54:55], 0, v[116:117]
	global_store_dwordx4 v[54:55], v[50:53], off
	s_nop 1
	v_add_u32_e32 v52, 0x90, v151
	v_mad_i64_i32 v[38:39], s[36:37], v52, s46, v[114:115]
	v_lshl_add_u64 v[38:39], v[38:39], 0, v[116:117]
	global_store_dwordx4 v[38:39], v[34:37], off
	s_nop 1
	v_add_u32_e32 v36, 0xa0, v151
	v_mad_i64_i32 v[22:23], s[36:37], v36, s46, v[114:115]
	v_lshl_add_u64 v[22:23], v[22:23], 0, v[116:117]
	global_store_dwordx4 v[22:23], v[18:21], off
	s_nop 1
	v_add_u32_e32 v20, 0xb0, v151
	v_mad_i64_i32 v[6:7], s[36:37], v20, s46, v[114:115]
	v_lshl_add_u64 v[6:7], v[6:7], 0, v[116:117]
	global_store_dwordx4 v[6:7], v[2:5], off
	s_cbranch_vccnz .LBB0_118
	s_andn2_b64 vcc, exec, s[6:7]
	s_cbranch_vccnz .LBB0_117
	s_barrier
	s_branch .LBB0_117
